# attention leading wave group: next tile's global loads issued in the QK->softmax accumulator-read gap instead of s_nop padding; iteration starts with LDS reads
# baseline (speedup 1.0000x reference)
; #define LAS __attribute__((address_space(3)))
; __device__ __forceinline__ int crow(int r, int hi) { return (r & 3) + 8 * (r >> 2) + 4 * hi; }
; __device__ __forceinline__ void attn_phase(const Ctx& c, const Params& p, int o, int first, int cidx) {
;     ...
;         for (int kt = 0; kt < ntile; ++kt) { const int kv0 = kt * 64; const int buf = kt & 1;
;             if (kt + 1 < ntile) { const int kn = kv0 + 64;
;                 rk0 = *(const u32x4*)(kg + (size_t)(kn + k0row) * 768 + 8 * k0ch); if (k1on) rk1 = *(const u32x4*)(kg + (size_t)(kn + k1row) * 768 + 8 * k1ch); rv = *(const u32x4*)(vg + (size_t)vrow * T_ + kn + 8 * vch); }
;             if (kv0 <= qs + 31) {
;                 const LAS bf16_t* kb = sK + buf * 6656 + l31 * 104 + 8 * hh; const LAS bf16_t* vb = sVt + buf * 4608 + l31 * 72 + 4 * hh;
;                 f32x16 p0 = {}, p1 = {};
; #pragma unroll
;                 for (int ks = 0; ks < 6; ++ks) { const bf16x8 k0 = *(const LAS bf16x8*)(kb + 16 * ks); const bf16x8 k1 = *(const LAS bf16x8*)(kb + 32 * 104 + 16 * ks);
;                     p0 = __builtin_amdgcn_mfma_f32_32x32x16_bf16(k0, qf[ks], p0, 0, 0, 0); p1 = __builtin_amdgcn_mfma_f32_32x32x16_bf16(k1, qf[ks], p1, 0, 0, 0); }
;                 if (kv0 + 63 > qs) { const int q = qs + l31;
; #pragma unroll
;                     for (int r = 0; r < 16; ++r) { const int kv = kv0 + crow(r, hh); if (kv > q) p0[r] = -INFINITY; if (kv + 32 > q) p1[r] = -INFINITY; } }
.LBB0_120:
	s_add_i32 s31, s10, 1
	s_cmp_lt_u32 s31, s27
	s_cselect_b64 s[2:3], -1, 0
	s_and_b32 s18, s10, 1
	s_cmp_gt_i32 s42, s29
	s_cbranch_scc1 .Lah_skip
	s_mul_i32 s10, s18, 0x3400
	s_mul_i32 s11, s18, 0x2400
	v_add_u32_e32 v1, s10, v130
	v_add_u32_e32 v142, s11, v131
	ds_read_b128 v[200:203], v1
	ds_read_b128 v[204:207], v1 offset:6656
	ds_read_b128 v[208:211], v1 offset:32
	ds_read_b128 v[212:215], v1 offset:6688
	ds_read_b128 v[216:219], v1 offset:64
	ds_read_b128 v[220:223], v1 offset:6720
	ds_read_b128 v[224:227], v1 offset:96
	ds_read_b128 v[228:231], v1 offset:6752
	ds_read_b128 v[232:235], v1 offset:128
	ds_read_b128 v[236:239], v1 offset:6784
	ds_read_b128 v[240:243], v1 offset:160
	ds_read_b128 v[244:247], v1 offset:6816
	v_add_u32_e32 v143, 0x7a00, v142
	v_add_u32_e32 v142, 0x6800, v142
	s_add_i32 s10, s42, 63
	s_cmp_le_i32 s10, s26
	s_waitcnt lgkmcnt(10)
	v_mfma_f32_32x32x16_bf16 v[50:65], v[200:203], v[66:69], 0
	v_mfma_f32_32x32x16_bf16 v[34:49], v[204:207], v[66:69], 0
	s_waitcnt lgkmcnt(8)
	v_mfma_f32_32x32x16_bf16 v[50:65], v[208:211], v[70:73], v[50:65]
	v_mfma_f32_32x32x16_bf16 v[34:49], v[212:215], v[70:73], v[34:49]
	s_waitcnt lgkmcnt(6)
	v_mfma_f32_32x32x16_bf16 v[50:65], v[216:219], v[74:77], v[50:65]
	v_mfma_f32_32x32x16_bf16 v[34:49], v[220:223], v[74:77], v[34:49]
	ds_read_b64 v[200:201], v142
	ds_read_b64 v[202:203], v142 offset:16
	ds_read_b64 v[204:205], v142 offset:32
	ds_read_b64 v[206:207], v142 offset:48
	s_waitcnt lgkmcnt(8)
	v_mfma_f32_32x32x16_bf16 v[50:65], v[224:227], v[78:81], v[50:65]
	v_mfma_f32_32x32x16_bf16 v[34:49], v[228:231], v[78:81], v[34:49]
	ds_read_b64 v[208:209], v142 offset:64
	ds_read_b64 v[210:211], v142 offset:80
	ds_read_b64 v[212:213], v142 offset:96
	ds_read_b64 v[214:215], v142 offset:112
	s_waitcnt lgkmcnt(10)
	v_mfma_f32_32x32x16_bf16 v[50:65], v[232:235], v[82:85], v[50:65]
	v_mfma_f32_32x32x16_bf16 v[34:49], v[236:239], v[82:85], v[34:49]
	ds_read_b64 v[216:217], v143
	ds_read_b64 v[218:219], v143 offset:16
	ds_read_b64 v[220:221], v143 offset:32
	ds_read_b64 v[222:223], v143 offset:48
	s_waitcnt lgkmcnt(12)
	v_mfma_f32_32x32x16_bf16 v[50:65], v[240:243], v[86:89], v[50:65]
	v_mfma_f32_32x32x16_bf16 v[34:49], v[244:247], v[86:89], v[34:49]
	ds_read_b64 v[224:225], v143 offset:64
	ds_read_b64 v[226:227], v143 offset:80
	ds_read_b64 v[228:229], v143 offset:96
	s_waitcnt lgkmcnt(7)
	ds_read_b64 v[230:231], v143 offset:112
	s_cbranch_scc1 .LBB0_127
	v_add_u32_e32 v1, s42, v112
	v_add_u32_e32 v138, 32, v1
	v_cmp_le_i32_e32 vcc, v138, v135
	v_add_u32_e32 v138, 33, v1
	s_nop 6
	v_cndmask_b32_e32 v34, v173, v34, vcc
	v_cmp_lt_i32_e32 vcc, v1, v135
	s_nop 1
	v_cndmask_b32_e32 v51, v173, v51, vcc
	v_cmp_le_i32_e32 vcc, v1, v135
	s_nop 1
	v_cndmask_b32_e32 v50, v173, v50, vcc
	v_cmp_le_i32_e32 vcc, v138, v135
	v_add_u32_e32 v138, 2, v1
	s_nop 0
	v_cndmask_b32_e32 v35, v173, v35, vcc
	v_cmp_le_i32_e32 vcc, v138, v135
	v_add_u32_e32 v138, 34, v1
	s_nop 0
	v_cndmask_b32_e32 v52, v173, v52, vcc
	v_cmp_le_i32_e32 vcc, v138, v135
	v_add_u32_e32 v138, 3, v1
	s_nop 0
	v_cndmask_b32_e32 v36, v173, v36, vcc
	v_cmp_le_i32_e32 vcc, v138, v135
	v_add_u32_e32 v138, 35, v1
	s_nop 0
	v_cndmask_b32_e32 v53, v173, v53, vcc
	v_cmp_le_i32_e32 vcc, v138, v135
	v_add_u32_e32 v138, 8, v1
	s_nop 0
	v_cndmask_b32_e32 v37, v173, v37, vcc
	v_cmp_le_i32_e32 vcc, v138, v135
	v_add_u32_e32 v138, 40, v1
	s_nop 0
	v_cndmask_b32_e32 v54, v173, v54, vcc
	v_cmp_le_i32_e32 vcc, v138, v135
	v_add_u32_e32 v138, 9, v1
	s_nop 0
	v_cndmask_b32_e32 v38, v173, v38, vcc
	v_cmp_le_i32_e32 vcc, v138, v135
	v_add_u32_e32 v138, 41, v1
	s_nop 0
	v_cndmask_b32_e32 v55, v173, v55, vcc
	v_cmp_le_i32_e32 vcc, v138, v135
	v_add_u32_e32 v138, 10, v1
	s_nop 0
	v_cndmask_b32_e32 v39, v173, v39, vcc
	v_cmp_le_i32_e32 vcc, v138, v135
	v_add_u32_e32 v138, 42, v1
	s_nop 0
	v_cndmask_b32_e32 v56, v173, v56, vcc
	v_cmp_le_i32_e32 vcc, v138, v135
	v_add_u32_e32 v138, 11, v1
	s_nop 0
	v_cndmask_b32_e32 v40, v173, v40, vcc
	v_cmp_le_i32_e32 vcc, v138, v135
	v_add_u32_e32 v138, 43, v1
	s_nop 0
	v_cndmask_b32_e32 v57, v173, v57, vcc
	v_cmp_le_i32_e32 vcc, v138, v135
	v_add_u32_e32 v138, 16, v1
	s_nop 0
	v_cndmask_b32_e32 v41, v173, v41, vcc
	v_cmp_le_i32_e32 vcc, v138, v135
	v_add_u32_e32 v138, 48, v1
	s_nop 0
	v_cndmask_b32_e32 v58, v173, v58, vcc
	v_cmp_le_i32_e32 vcc, v138, v135
	v_add_u32_e32 v138, 17, v1
	s_nop 0
	v_cndmask_b32_e32 v42, v173, v42, vcc
	v_cmp_le_i32_e32 vcc, v138, v135
	v_add_u32_e32 v138, 49, v1
	s_nop 0
	v_cndmask_b32_e32 v59, v173, v59, vcc
	v_cmp_le_i32_e32 vcc, v138, v135
	v_add_u32_e32 v138, 18, v1
	s_nop 0
	v_cndmask_b32_e32 v43, v173, v43, vcc
	v_cmp_le_i32_e32 vcc, v138, v135
	v_add_u32_e32 v138, 50, v1
	s_nop 0
	v_cndmask_b32_e32 v60, v173, v60, vcc
	v_cmp_le_i32_e32 vcc, v138, v135
	v_add_u32_e32 v138, 19, v1
	s_nop 0
	v_cndmask_b32_e32 v44, v173, v44, vcc
	v_cmp_le_i32_e32 vcc, v138, v135
	v_add_u32_e32 v138, 51, v1
	s_nop 0
	v_cndmask_b32_e32 v61, v173, v61, vcc
	v_cmp_le_i32_e32 vcc, v138, v135
	v_add_u32_e32 v138, 24, v1
	s_nop 0
	v_cndmask_b32_e32 v45, v173, v45, vcc
	v_cmp_le_i32_e32 vcc, v138, v135
	v_add_u32_e32 v138, 56, v1
	s_nop 0
	v_cndmask_b32_e32 v62, v173, v62, vcc
	v_cmp_le_i32_e32 vcc, v138, v135
	v_add_u32_e32 v138, 25, v1
	s_nop 0
	v_cndmask_b32_e32 v46, v173, v46, vcc
	v_cmp_le_i32_e32 vcc, v138, v135
	v_add_u32_e32 v138, 57, v1
	s_nop 0
	v_cndmask_b32_e32 v63, v173, v63, vcc
	v_cmp_le_i32_e32 vcc, v138, v135
	v_add_u32_e32 v138, 26, v1
	s_nop 0
	v_cndmask_b32_e32 v47, v173, v47, vcc
	v_cmp_le_i32_e32 vcc, v138, v135
	v_add_u32_e32 v138, 58, v1
	s_nop 0
	v_cndmask_b32_e32 v64, v173, v64, vcc
	v_cmp_le_i32_e32 vcc, v138, v135
	v_add_u32_e32 v138, 27, v1
	v_add_u32_e32 v1, 59, v1
	v_cndmask_b32_e32 v48, v173, v48, vcc
	v_cmp_le_i32_e32 vcc, v138, v135
	s_nop 1
	v_cndmask_b32_e32 v65, v173, v65, vcc
	v_cmp_le_i32_e32 vcc, v1, v135
	s_nop 1
	v_cndmask_b32_e32 v49, v173, v49, vcc
.LBB0_127:
	s_andn2_b64 vcc, exec, s[2:3]
	s_cbranch_vccnz .Lah_nonext
	v_add_u32_e32 v250, s42, v133
	v_mad_i64_i32 v[248:249], s[10:11], v250, s50, v[120:121]
	global_load_dwordx4 v[90:93], v[248:249], off
	v_add_u32_e32 v250, s42, v132
	v_mad_i64_i32 v[248:249], s[10:11], v250, s50, v[122:123]
	global_load_dwordx4 v[94:97], v[248:249], off
	v_lshl_add_u64 v[248:249], s[42:43], 1, v[118:119]
	global_load_dwordx4 v[98:101], v[248:249], off offset:128
	s_nop 3
	s_branch .Lah_sm

; __device__ __forceinline__ void attn_phase(const Ctx& c, const Params& p, int o, int first, int cidx) {
;     ...
;                 float mxa = fmaxf(fmaxf(p0[0], p1[0]), p0[1]), mxb = fmaxf(fmaxf(p1[1], p0[2]), p1[2]);
; #pragma unroll
;                 for (int r = 3; r < 15; r += 2) { mxa = fmaxf(fmaxf(mxa, p0[r]), p1[r]); mxb = fmaxf(fmaxf(mxb, p0[r + 1]), p1[r + 1]); }
;                 float mx = fmaxf(fmaxf(mxa, mxb), fmaxf(p0[15], p1[15]));
;                 { auto rr = __builtin_amdgcn_permlane32_swap(asu(mx), asu(mx), false, false); mx = fmaxf(asf(rr[0]), asf(rr[1])); }
;                 const float mnew = fmaxf(mrun, mx);
;                 if (__any(mnew > mrun)) { const float alpha = __builtin_amdgcn_exp2f(mrun - mnew); lrun *= alpha; o0 = o0 * alpha; o1 = o1 * alpha; }
.Lah_sm:
	v_max3_f32 v1, v50, v34, v51
	v_max3_f32 v138, v35, v52, v36
	v_max3_f32 v1, v1, v53, v37
	v_max3_f32 v138, v138, v54, v38
	v_max3_f32 v1, v1, v55, v39
	v_max3_f32 v138, v138, v56, v40
	v_max3_f32 v1, v1, v57, v41
	v_max3_f32 v138, v138, v58, v42
	v_max3_f32 v1, v1, v59, v43
	v_max3_f32 v138, v138, v60, v44
	v_max3_f32 v1, v1, v61, v45
	v_max3_f32 v138, v138, v62, v46
	v_max_f32_e32 v139, v49, v49
	v_max_f32_e32 v140, v65, v65
	v_max3_f32 v1, v1, v63, v47
	v_max3_f32 v138, v138, v64, v48
	v_max_f32_e32 v139, v140, v139
	v_max3_f32 v1, v1, v138, v139
	v_mov_b32_e32 v138, v1
	s_nop 1
	v_permlane32_swap_b32_e32 v1, v138
	v_max3_f32 v1, v137, v1, v138
	v_cmp_gt_f32_e32 vcc, v1, v137
	s_cbranch_vccz .LBB0_129
	v_sub_f32_e32 v137, v137, v1
	v_exp_f32_e32 v138, v137
	s_nop 0
	v_mul_f32_e32 v136, v136, v138
	v_mul_f32_e32 v32, v138, v32
	v_mul_f32_e32 v33, v138, v33
	v_mul_f32_e32 v30, v138, v30
	v_mul_f32_e32 v31, v138, v31
	v_mul_f32_e32 v28, v138, v28
	v_mul_f32_e32 v29, v138, v29
	v_mul_f32_e32 v26, v138, v26
	v_mul_f32_e32 v27, v138, v27
	v_mul_f32_e32 v24, v138, v24
	v_mul_f32_e32 v25, v138, v25
	v_mul_f32_e32 v22, v138, v22
	v_mul_f32_e32 v23, v138, v23
	v_mul_f32_e32 v20, v138, v20
	v_mul_f32_e32 v21, v138, v21
	v_mul_f32_e32 v18, v138, v18
	v_mul_f32_e32 v19, v138, v19
	v_mul_f32_e32 v16, v138, v16
	v_mul_f32_e32 v17, v138, v17
	v_mul_f32_e32 v14, v138, v14
	v_mul_f32_e32 v15, v138, v15
	v_mul_f32_e32 v12, v138, v12
	v_mul_f32_e32 v13, v138, v13
	v_mul_f32_e32 v10, v138, v10
	v_mul_f32_e32 v11, v138, v11
	v_mul_f32_e32 v8, v138, v8
	v_mul_f32_e32 v9, v138, v9
	v_mul_f32_e32 v6, v138, v6
	v_mul_f32_e32 v7, v138, v7
	v_mul_f32_e32 v4, v138, v4
	v_mul_f32_e32 v5, v138, v5
	v_mul_f32_e32 v2, v138, v2
	v_mul_f32_e32 v3, v138, v3

; __device__ __forceinline__ void attn_phase(const Ctx& c, const Params& p, int o, int first, int cidx) {
;     ...
;             if (kt + 1 < ntile) { const int kn = kv0 + 64;
;                 rk0 = *(const u32x4*)(kg + (size_t)(kn + k0row) * 768 + 8 * k0ch); if (k1on) rk1 = *(const u32x4*)(kg + (size_t)(kn + k1row) * 768 + 8 * k1ch); rv = *(const u32x4*)(vg + (size_t)vrow * T_ + kn + 8 * vch); }
;     ...
;             if (kt + 1 < ntile) { const int nb = buf ^ 1;
.Lah_skip:
	s_andn2_b64 vcc, exec, s[2:3]
	s_cbranch_vccnz .LBB0_130
	v_add_u32_e32 v250, s42, v133
	v_mad_i64_i32 v[248:249], s[10:11], v250, s50, v[120:121]
	global_load_dwordx4 v[90:93], v[248:249], off
	v_add_u32_e32 v250, s42, v132
	v_mad_i64_i32 v[248:249], s[10:11], v250, s50, v[122:123]
	global_load_dwordx4 v[94:97], v[248:249], off
	v_lshl_add_u64 v[248:249], s[42:43], 1, v[118:119]
	global_load_dwordx4 v[98:101], v[248:249], off offset:128
